# phase 12 K-loop restructured: 4 barrier intervals per K-tile (32 MFMA per interval, 16/8 LDS reads, staging 2/6) instead of 8
# baseline (speedup 1.0000x reference)
; #define PG8_STAGE(bufoff, gbase, voff) do { _Pragma("unroll") for (int _i = 0; _i < 2; ++_i) \
;         __builtin_amdgcn_global_load_lds((const unsigned*)((const char*)(gbase) + (voff)[_i]), (LAS unsigned*)(lds + (bufoff) + ldsw + _i * 8192), 16, 0, 0); } while (0)
; #define PG8_WAIT_V(n) asm volatile("s_waitcnt vmcnt(" #n ")" ::: "memory")
; #define PG8_BAR __builtin_amdgcn_s_barrier()
; template <class Epi, class Sched>
; __device__ __forceinline__ void gemm_phase(LAS unsigned char* lds, const Gemm g, const Sched& S, const Epi& E) {
;     ...
;     for (int i = 0; i < 2; ++i) { int R, C; stage_rc(tid * 16 + i * 8192, R, C); const int Rb = Epi::PERM ? ((R & ~31) + perm32(R & 31)) : R;
;         voffA[i] = (unsigned)(R * g.lda + C) * 2u; voffB[i] = (unsigned)(Rb * g.ldb + C) * 2u; }
;     const size_t kstep = (size_t)(BK * 2);
;     const size_t hstepA = g.a_half ? g.a_half : (size_t)HALF * g.lda * 2, hstepB = g.b_half ? g.b_half : (size_t)HALF * g.ldb * 2;
;     const size_t tstepA = g.a_tile ? g.a_tile : (size_t)BM * g.lda * 2, tstepB = g.b_tile ? g.b_tile : (size_t)BM * g.ldb * 2;
;     const unsigned ldsw = (unsigned)wid * 1024u;
;     const int aoff = lds_byte(wr * 64 + fr, fq * 8), boff = lds_byte(wc * 32 + fr, fq * 8);
;     ...
;     PG8_STAGE(PG8_SB(0, 0), cB, voffB); PG8_STAGE(PG8_SA(0, 0), cA, voffA); PG8_STAGE(PG8_SB(0, 1), cB + hstepB, voffB); PG8_STAGE(PG8_SA(0, 1), cA + hstepA, voffA);
;     if (wr == 1) PG8_BAR;
;     PG8_WAIT_V(4); PG8_BAR;
;     PG8_STAGE(PG8_SB(1, 0), cB + kstep, voffB); PG8_STAGE(PG8_SA(1, 0), cA + kstep, voffA); PG8_STAGE(PG8_SB(1, 1), cB + hstepB + kstep, voffB);
;     PG8_WAIT_V(6); PG8_BAR;
.LBB0_1839:
	s_add_u32 s8, s84, 0x11d39000
	s_addc_u32 s9, s85, 0
	s_lshl_b32 s10, s10, 5
	s_and_b32 s15, s10, 0x60
	s_mov_b64 s[10:11], 0x80
	s_add_i32 m0, s21, 0x18000
	v_lshl_add_u64 v[6:7], v[6:7], 0, s[10:11]
	s_ashr_i32 s41, s96, 31
	s_lshl_b32 s14, s7, 13
	s_lshl_b32 s16, s15, 7
	s_waitcnt vmcnt(2)
	s_barrier
	global_load_lds_dwordx4 v[6:7], off
	v_lshl_add_u64 v[4:5], v[4:5], 0, s[10:11]
	s_add_i32 m0, s21, 0x1a000
	s_add_i32 s42, s21, 0x8000
	s_add_i32 s43, s21, 0xa000
	global_load_lds_dwordx4 v[4:5], off
	v_lshl_add_u64 v[2:3], v[2:3], 0, s[10:11]
	s_mov_b32 m0, s42
	s_add_u32 s12, s24, 0x80080
	global_load_lds_dwordx4 v[2:3], off
	v_lshl_add_u64 v[0:1], v[0:1], 0, s[10:11]
	s_mov_b32 m0, s43
	s_addc_u32 s13, s25, 0
	global_load_lds_dwordx4 v[0:1], off
	s_add_i32 m0, s21, 0x1c000
	v_lshl_add_u64 v[0:1], s[12:13], 0, v[130:131]
	global_load_lds_dwordx4 v[0:1], off
	v_lshl_add_u64 v[0:1], s[12:13], 0, v[134:135]
	s_add_i32 m0, s21, 0x1e000
	s_sext_i32_i16 s47, s6
	global_load_lds_dwordx4 v[0:1], off
	v_and_b32_e32 v0, 15, v160
	v_lshlrev_b32_e32 v1, 1, v11
	v_lshlrev_b32_e32 v2, 6, v160
	s_movk_i32 s6, 0x3c0
	v_and_or_b32 v2, v2, s6, v1
	v_and_b32_e32 v3, 32, v184
	v_lshl_or_b32 v144, s7, 6, v0
	v_lshl_or_b32 v0, v0, 6, v1
	v_lshlrev_b32_e32 v1, 9, v160
	v_bitop3_b32 v145, s16, v2, v3 bitop3:0xf6
	v_and_b32_e32 v1, 0x70000, v1
	v_lshlrev_b32_e32 v2, 12, v10
	v_or3_b32 v1, v8, v1, v2
	v_add_u32_e32 v136, v1, v9
	v_lshlrev_b32_e32 v1, 5, v12
	s_waitcnt vmcnt(6)
	v_and_b32_e32 v1, 0xf0000, v1
	v_bitop3_b32 v0, v0, s14, v3 bitop3:0xde
	v_or3_b32 v1, v8, v1, v2
	s_add_i32 s44, 0, 0x10000
	s_add_i32 s45, 0, 0x14000
	v_or_b32_e32 v146, s15, v11
	v_mov_b32_e32 v137, v131
	v_add_u32_e32 v138, v1, v9
	v_mov_b32_e32 v139, v131
	v_mov_b64_e32 v[140:141], 0x5d8
	v_mov_b64_e32 v[142:143], 0x5d7
	v_add_u32_e32 v147, s44, v145
	v_add_u32_e32 v148, 0, v0
	v_add_u32_e32 v149, s45, v145
	s_movk_i32 s46, 0x2c00
	s_barrier

; #define PG8_STAGE(bufoff, gbase, voff) do { _Pragma("unroll") for (int _i = 0; _i < 2; ++_i) \
;         __builtin_amdgcn_global_load_lds((const unsigned*)((const char*)(gbase) + (voff)[_i]), (LAS unsigned*)(lds + (bufoff) + ldsw + _i * 8192), 16, 0, 0); } while (0)
; #define PG8_LDA(dst, b, h) do { _Pragma("unroll") for (int m = 0; m < 4; ++m) _Pragma("unroll") for (int k = 0; k < 2; ++k) dst[m][k] = *(const LAS bf16x8*)(lds + PG8_SA(b, h) + aoff + m * 2048 + k * 1024); } while (0)
; #define PG8_LDB(dst, b, h) do { _Pragma("unroll") for (int n = 0; n < 2; ++n) _Pragma("unroll") for (int k = 0; k < 2; ++k) dst[n][k] = *(const LAS bf16x8*)(lds + PG8_SB(b, h) + boff + n * 2048 + k * 1024); } while (0)
; #define PG8_MMA(ai, bj, At, Bt) do { __builtin_amdgcn_s_setprio(1); _Pragma("unroll") for (int m = 0; m < 4; ++m) _Pragma("unroll") for (int n = 0; n < 2; ++n) _Pragma("unroll") for (int k = 0; k < 2; ++k) \
;         acc[ai][bj][m][n] = __builtin_amdgcn_mfma_f32_16x16x32_bf16(Bt[n][k], At[m][k], acc[ai][bj][m][n], 0, 0, 0); __builtin_amdgcn_s_setprio(0); } while (0)
; #define PG8_WAIT_V(n) asm volatile("s_waitcnt vmcnt(" #n ")" ::: "memory")
; #define PG8_WAIT_L(n) asm volatile("s_waitcnt lgkmcnt(" #n ")" ::: "memory")
; #define PG8_BAR __builtin_amdgcn_s_barrier()
; #define PG8_SCHED __builtin_amdgcn_sched_barrier(0)
; template <class Epi, class Sched>
; __device__ __forceinline__ void gemm_phase(LAS unsigned char* lds, const Gemm g, const Sched& S, const Epi& E) {
;     ...
;             PG8_LDB(B0, 0, 0); PG8_SCHED; PG8_LDA(At, 0, 0); PG8_STAGE(PG8_SA(1, 1), a1 + hstepA, voffA);
;             PG8_WAIT_L(8); PG8_BAR; PG8_WAIT_L(0); PG8_MMA(0, 0, At, B0); PG8_BAR; PG8_SCHED;
;             PG8_LDB(B1, 0, 1); PG8_STAGE(PG8_SB(0, 0), b2, voffB);
;             PG8_BAR; PG8_WAIT_L(0); if constexpr (!Epi::DIAG) PG8_MMA(0, 1, At, B1); PG8_BAR;
;             PG8_LDA(At, 0, 1); PG8_STAGE(PG8_SA(0, 0), a2, voffA);
;             PG8_BAR; PG8_WAIT_L(0); if constexpr (!Epi::DIAG) PG8_MMA(1, 0, At, B0); PG8_BAR; PG8_SCHED;
;             PG8_STAGE(PG8_SB(0, 1), b2 + hstepB, voffB);
;             PG8_WAIT_V(6); PG8_BAR; PG8_MMA(1, 1, At, B1); PG8_BAR;
.LBB0_1843:
	ds_read_b128 v[150:153], v147
	ds_read_b128 v[154:157], v147 offset:1024
	ds_read_b128 v[162:165], v147 offset:2048
	ds_read_b128 v[166:169], v147 offset:3072
	s_add_u32 s24, s22, 0xfff80080
	s_addc_u32 s25, s23, -1
	s_cmp_eq_u32 s52, 28
	s_cselect_b32 s27, s15, s25
	s_cselect_b32 s26, s48, s24
	s_cselect_b32 s25, s13, s51
	s_cselect_b32 s24, s49, s50
	v_lshl_add_u64 v[158:159], s[22:23], 0, v[136:137]
	s_add_i32 m0, s21, 0xc000
	ds_read_b128 v[170:173], v148
	ds_read_b128 v[174:177], v148 offset:1024
	ds_read_b128 v[178:181], v148 offset:2048
	ds_read_b128 v[186:189], v148 offset:3072
	ds_read_b128 v[190:193], v148 offset:4096
	ds_read_b128 v[194:197], v148 offset:5120
	ds_read_b128 v[198:201], v148 offset:6144
	ds_read_b128 v[202:205], v148 offset:7168
	global_load_lds_dwordx4 v[158:159], off
	v_lshl_add_u64 v[158:159], s[22:23], 0, v[138:139]
	s_add_i32 m0, s21, 0xe000
	s_nop 0
	global_load_lds_dwordx4 v[158:159], off
	ds_read_b128 v[206:209], v149
	ds_read_b128 v[210:213], v149 offset:1024
	ds_read_b128 v[214:217], v149 offset:2048
	ds_read_b128 v[218:221], v149 offset:3072
	s_waitcnt vmcnt(8)
	s_barrier
	s_waitcnt lgkmcnt(0)
	s_setprio 1
	v_mfma_f32_16x16x32_bf16 v[124:127], v[150:153], v[170:173], v[124:127]
	v_mfma_f32_16x16x32_bf16 v[116:119], v[162:165], v[170:173], v[116:119]
	v_mfma_f32_16x16x32_bf16 v[108:111], v[150:153], v[178:181], v[108:111]
	v_mfma_f32_16x16x32_bf16 v[100:103], v[162:165], v[178:181], v[100:103]
	v_mfma_f32_16x16x32_bf16 v[92:95], v[150:153], v[190:193], v[92:95]
	v_mfma_f32_16x16x32_bf16 v[84:87], v[162:165], v[190:193], v[84:87]
	v_mfma_f32_16x16x32_bf16 v[76:79], v[150:153], v[198:201], v[76:79]
	v_mfma_f32_16x16x32_bf16 v[68:71], v[162:165], v[198:201], v[68:71]
	v_mfma_f32_16x16x32_bf16 v[124:127], v[154:157], v[174:177], v[124:127]
	v_mfma_f32_16x16x32_bf16 v[116:119], v[166:169], v[174:177], v[116:119]
	v_mfma_f32_16x16x32_bf16 v[108:111], v[154:157], v[186:189], v[108:111]
	v_mfma_f32_16x16x32_bf16 v[100:103], v[166:169], v[186:189], v[100:103]
	v_mfma_f32_16x16x32_bf16 v[92:95], v[154:157], v[194:197], v[92:95]
	v_mfma_f32_16x16x32_bf16 v[84:87], v[166:169], v[194:197], v[84:87]
	v_mfma_f32_16x16x32_bf16 v[76:79], v[154:157], v[202:205], v[76:79]
	v_mfma_f32_16x16x32_bf16 v[68:71], v[166:169], v[202:205], v[68:71]
	v_mfma_f32_16x16x32_bf16 v[120:123], v[206:209], v[170:173], v[120:123]
	v_mfma_f32_16x16x32_bf16 v[112:115], v[214:217], v[170:173], v[112:115]
	v_mfma_f32_16x16x32_bf16 v[104:107], v[206:209], v[178:181], v[104:107]
	v_mfma_f32_16x16x32_bf16 v[96:99], v[214:217], v[178:181], v[96:99]
	v_mfma_f32_16x16x32_bf16 v[88:91], v[206:209], v[190:193], v[88:91]
	v_mfma_f32_16x16x32_bf16 v[80:83], v[214:217], v[190:193], v[80:83]
	v_mfma_f32_16x16x32_bf16 v[72:75], v[206:209], v[198:201], v[72:75]
	v_mfma_f32_16x16x32_bf16 v[64:67], v[214:217], v[198:201], v[64:67]
	v_mfma_f32_16x16x32_bf16 v[120:123], v[210:213], v[174:177], v[120:123]
	v_mfma_f32_16x16x32_bf16 v[112:115], v[218:221], v[174:177], v[112:115]
	v_mfma_f32_16x16x32_bf16 v[104:107], v[210:213], v[186:189], v[104:107]
	v_mfma_f32_16x16x32_bf16 v[96:99], v[218:221], v[186:189], v[96:99]
	v_mfma_f32_16x16x32_bf16 v[88:91], v[210:213], v[194:197], v[88:91]
	v_mfma_f32_16x16x32_bf16 v[80:83], v[218:221], v[194:197], v[80:83]
	v_mfma_f32_16x16x32_bf16 v[72:75], v[210:213], v[202:205], v[72:75]
	v_mfma_f32_16x16x32_bf16 v[64:67], v[218:221], v[202:205], v[64:67]
	s_setprio 0
	s_barrier
	ds_read_b128 v[170:173], v148 offset:16384
	ds_read_b128 v[174:177], v148 offset:17408
	ds_read_b128 v[178:181], v148 offset:18432
	ds_read_b128 v[186:189], v148 offset:19456
	ds_read_b128 v[190:193], v148 offset:20480
	ds_read_b128 v[194:197], v148 offset:21504
	ds_read_b128 v[198:201], v148 offset:22528
	ds_read_b128 v[202:205], v148 offset:23552
	s_add_i32 s53, s44, s34
	v_lshl_add_u64 v[158:159], s[24:25], 0, v[130:131]
	s_mov_b32 m0, s53
	s_nop 0
	global_load_lds_dwordx4 v[158:159], off
	v_lshl_add_u64 v[182:183], s[24:25], 0, v[134:135]
	s_add_i32 m0, s53, 0x2000
	s_nop 0
	global_load_lds_dwordx4 v[182:183], off
	s_mov_b32 m0, s21
	v_lshl_add_u64 v[222:223], s[26:27], 0, v[128:129]
	global_load_lds_dwordx4 v[222:223], off
	v_lshl_add_u64 v[224:225], s[26:27], 0, v[132:133]
	s_mov_b32 m0, s37
	s_nop 0
	global_load_lds_dwordx4 v[224:225], off
	s_add_u32 s54, s24, 0x80000
	s_addc_u32 s55, s25, 0
	s_add_i32 s53, s45, s34
	v_lshl_add_u64 v[230:231], s[54:55], 0, v[130:131]
	s_mov_b32 m0, s53
	s_nop 0
	global_load_lds_dwordx4 v[230:231], off
	v_lshl_add_u64 v[230:231], s[54:55], 0, v[134:135]
	s_add_i32 m0, s53, 0x2000
	s_nop 0
	global_load_lds_dwordx4 v[230:231], off
	s_waitcnt vmcnt(8)
	s_barrier
; #define PG8_STAGE(bufoff, gbase, voff) do { _Pragma("unroll") for (int _i = 0; _i < 2; ++_i) \
;         __builtin_amdgcn_global_load_lds((const unsigned*)((const char*)(gbase) + (voff)[_i]), (LAS unsigned*)(lds + (bufoff) + ldsw + _i * 8192), 16, 0, 0); } while (0)
; #define PG8_LDA(dst, b, h) do { _Pragma("unroll") for (int m = 0; m < 4; ++m) _Pragma("unroll") for (int k = 0; k < 2; ++k) dst[m][k] = *(const LAS bf16x8*)(lds + PG8_SA(b, h) + aoff + m * 2048 + k * 1024); } while (0)
; #define PG8_LDB(dst, b, h) do { _Pragma("unroll") for (int n = 0; n < 2; ++n) _Pragma("unroll") for (int k = 0; k < 2; ++k) dst[n][k] = *(const LAS bf16x8*)(lds + PG8_SB(b, h) + boff + n * 2048 + k * 1024); } while (0)
; #define PG8_MMA(ai, bj, At, Bt) do { __builtin_amdgcn_s_setprio(1); _Pragma("unroll") for (int m = 0; m < 4; ++m) _Pragma("unroll") for (int n = 0; n < 2; ++n) _Pragma("unroll") for (int k = 0; k < 2; ++k) \
;         acc[ai][bj][m][n] = __builtin_amdgcn_mfma_f32_16x16x32_bf16(Bt[n][k], At[m][k], acc[ai][bj][m][n], 0, 0, 0); __builtin_amdgcn_s_setprio(0); } while (0)
; #define PG8_WAIT_V(n) asm volatile("s_waitcnt vmcnt(" #n ")" ::: "memory")
; #define PG8_WAIT_L(n) asm volatile("s_waitcnt lgkmcnt(" #n ")" ::: "memory")
; #define PG8_BAR __builtin_amdgcn_s_barrier()
; #define PG8_SCHED __builtin_amdgcn_sched_barrier(0)
; template <class Epi, class Sched>
; __device__ __forceinline__ void gemm_phase(LAS unsigned char* lds, const Gemm g, const Sched& S, const Epi& E) {
;     ...
;             PG8_BAR; PG8_WAIT_L(0); if constexpr (!Epi::DIAG) PG8_MMA(1, 0, At, B0); PG8_BAR; PG8_SCHED;
;             PG8_STAGE(PG8_SB(0, 1), b2 + hstepB, voffB);
;             PG8_WAIT_V(6); PG8_BAR; PG8_MMA(1, 1, At, B1); PG8_BAR;
;             PG8_LDB(B0, 1, 0); PG8_SCHED; PG8_LDA(At, 1, 0); PG8_STAGE(PG8_SA(0, 1), a2 + hstepA, voffA);
;             PG8_WAIT_L(8); PG8_BAR; PG8_WAIT_L(0); PG8_MMA(0, 0, At, B0); PG8_BAR; PG8_SCHED;
;             PG8_LDB(B1, 1, 1); PG8_STAGE(PG8_SB(1, 0), b3, voffB);
;             PG8_BAR; PG8_WAIT_L(0); if constexpr (!Epi::DIAG) PG8_MMA(0, 1, At, B1); PG8_BAR;
	s_waitcnt lgkmcnt(0)
	s_setprio 1
	v_mfma_f32_16x16x32_bf16 v[60:63], v[150:153], v[170:173], v[60:63]
	v_mfma_f32_16x16x32_bf16 v[52:55], v[162:165], v[170:173], v[52:55]
	v_mfma_f32_16x16x32_bf16 v[44:47], v[150:153], v[178:181], v[44:47]
	v_mfma_f32_16x16x32_bf16 v[36:39], v[162:165], v[178:181], v[36:39]
	v_mfma_f32_16x16x32_bf16 v[28:31], v[150:153], v[190:193], v[28:31]
	v_mfma_f32_16x16x32_bf16 v[20:23], v[162:165], v[190:193], v[20:23]
	v_mfma_f32_16x16x32_bf16 v[12:15], v[150:153], v[198:201], v[12:15]
	v_mfma_f32_16x16x32_bf16 v[4:7], v[162:165], v[198:201], v[4:7]
	v_mfma_f32_16x16x32_bf16 v[60:63], v[154:157], v[174:177], v[60:63]
	v_mfma_f32_16x16x32_bf16 v[52:55], v[166:169], v[174:177], v[52:55]
	v_mfma_f32_16x16x32_bf16 v[44:47], v[154:157], v[186:189], v[44:47]
	v_mfma_f32_16x16x32_bf16 v[36:39], v[166:169], v[186:189], v[36:39]
	v_mfma_f32_16x16x32_bf16 v[28:31], v[154:157], v[194:197], v[28:31]
	v_mfma_f32_16x16x32_bf16 v[20:23], v[166:169], v[194:197], v[20:23]
	v_mfma_f32_16x16x32_bf16 v[12:15], v[154:157], v[202:205], v[12:15]
	v_mfma_f32_16x16x32_bf16 v[4:7], v[166:169], v[202:205], v[4:7]
	v_mfma_f32_16x16x32_bf16 v[56:59], v[206:209], v[170:173], v[56:59]
	v_mfma_f32_16x16x32_bf16 v[48:51], v[214:217], v[170:173], v[48:51]
	v_mfma_f32_16x16x32_bf16 v[40:43], v[206:209], v[178:181], v[40:43]
	v_mfma_f32_16x16x32_bf16 v[32:35], v[214:217], v[178:181], v[32:35]
	v_mfma_f32_16x16x32_bf16 v[24:27], v[206:209], v[190:193], v[24:27]
	v_mfma_f32_16x16x32_bf16 v[16:19], v[214:217], v[190:193], v[16:19]
	v_mfma_f32_16x16x32_bf16 v[8:11], v[206:209], v[198:201], v[8:11]
	v_mfma_f32_16x16x32_bf16 v[0:3], v[214:217], v[198:201], v[0:3]
	v_mfma_f32_16x16x32_bf16 v[56:59], v[210:213], v[174:177], v[56:59]
	v_mfma_f32_16x16x32_bf16 v[48:51], v[218:221], v[174:177], v[48:51]
	v_mfma_f32_16x16x32_bf16 v[40:43], v[210:213], v[186:189], v[40:43]
	v_mfma_f32_16x16x32_bf16 v[32:35], v[218:221], v[186:189], v[32:35]
	v_mfma_f32_16x16x32_bf16 v[24:27], v[210:213], v[194:197], v[24:27]
	v_mfma_f32_16x16x32_bf16 v[16:19], v[218:221], v[194:197], v[16:19]
	v_mfma_f32_16x16x32_bf16 v[8:11], v[210:213], v[202:205], v[8:11]
	v_mfma_f32_16x16x32_bf16 v[0:3], v[218:221], v[202:205], v[0:3]
	s_setprio 0
	s_barrier
	s_add_i32 s53, 0, 0x18000
	v_add_u32_e32 v161, s53, v145
	ds_read_b128 v[150:153], v161
	ds_read_b128 v[154:157], v161 offset:1024
	ds_read_b128 v[162:165], v161 offset:2048
	ds_read_b128 v[166:169], v161 offset:3072
	ds_read_b128 v[170:173], v148 offset:32768
	ds_read_b128 v[174:177], v148 offset:33792
	ds_read_b128 v[178:181], v148 offset:34816
	ds_read_b128 v[186:189], v148 offset:35840
	ds_read_b128 v[190:193], v148 offset:36864
	ds_read_b128 v[194:197], v148 offset:37888
	ds_read_b128 v[198:201], v148 offset:38912
	ds_read_b128 v[202:205], v148 offset:39936
	s_add_u32 s26, s26, 0x80000
	s_addc_u32 s27, s27, 0
	s_mov_b32 m0, s38
	v_lshl_add_u64 v[230:231], s[26:27], 0, v[128:129]
	global_load_lds_dwordx4 v[230:231], off
	v_lshl_add_u64 v[230:231], s[26:27], 0, v[132:133]
	s_mov_b32 m0, s39
	s_nop 0
	global_load_lds_dwordx4 v[230:231], off
	s_add_i32 s26, 0, 0x1c000
	s_add_i32 s27, s53, s34
	v_add_u32_e32 v161, s26, v145
	ds_read_b128 v[206:209], v161
	ds_read_b128 v[210:213], v161 offset:1024
	ds_read_b128 v[214:217], v161 offset:2048
	ds_read_b128 v[218:221], v161 offset:3072
	s_waitcnt vmcnt(8)
	s_barrier
	s_waitcnt lgkmcnt(0)
	s_setprio 1
	v_mfma_f32_16x16x32_bf16 v[124:127], v[150:153], v[170:173], v[124:127]
	v_mfma_f32_16x16x32_bf16 v[116:119], v[162:165], v[170:173], v[116:119]
	v_mfma_f32_16x16x32_bf16 v[108:111], v[150:153], v[178:181], v[108:111]
	v_mfma_f32_16x16x32_bf16 v[100:103], v[162:165], v[178:181], v[100:103]
	v_mfma_f32_16x16x32_bf16 v[92:95], v[150:153], v[190:193], v[92:95]
	v_mfma_f32_16x16x32_bf16 v[84:87], v[162:165], v[190:193], v[84:87]
	v_mfma_f32_16x16x32_bf16 v[76:79], v[150:153], v[198:201], v[76:79]
	v_mfma_f32_16x16x32_bf16 v[68:71], v[162:165], v[198:201], v[68:71]
	v_mfma_f32_16x16x32_bf16 v[124:127], v[154:157], v[174:177], v[124:127]
	v_mfma_f32_16x16x32_bf16 v[116:119], v[166:169], v[174:177], v[116:119]
	v_mfma_f32_16x16x32_bf16 v[108:111], v[154:157], v[186:189], v[108:111]
	v_mfma_f32_16x16x32_bf16 v[100:103], v[166:169], v[186:189], v[100:103]
	v_mfma_f32_16x16x32_bf16 v[92:95], v[154:157], v[194:197], v[92:95]
	v_mfma_f32_16x16x32_bf16 v[84:87], v[166:169], v[194:197], v[84:87]
	v_mfma_f32_16x16x32_bf16 v[76:79], v[154:157], v[202:205], v[76:79]
	v_mfma_f32_16x16x32_bf16 v[68:71], v[166:169], v[202:205], v[68:71]
	v_mfma_f32_16x16x32_bf16 v[120:123], v[206:209], v[170:173], v[120:123]
	v_mfma_f32_16x16x32_bf16 v[112:115], v[214:217], v[170:173], v[112:115]
	v_mfma_f32_16x16x32_bf16 v[104:107], v[206:209], v[178:181], v[104:107]
	v_mfma_f32_16x16x32_bf16 v[96:99], v[214:217], v[178:181], v[96:99]
	v_mfma_f32_16x16x32_bf16 v[88:91], v[206:209], v[190:193], v[88:91]
	v_mfma_f32_16x16x32_bf16 v[80:83], v[214:217], v[190:193], v[80:83]
	v_mfma_f32_16x16x32_bf16 v[72:75], v[206:209], v[198:201], v[72:75]
	v_mfma_f32_16x16x32_bf16 v[64:67], v[214:217], v[198:201], v[64:67]
	v_mfma_f32_16x16x32_bf16 v[120:123], v[210:213], v[174:177], v[120:123]
	v_mfma_f32_16x16x32_bf16 v[112:115], v[218:221], v[174:177], v[112:115]
	v_mfma_f32_16x16x32_bf16 v[104:107], v[210:213], v[186:189], v[104:107]
	v_mfma_f32_16x16x32_bf16 v[96:99], v[218:221], v[186:189], v[96:99]
	v_mfma_f32_16x16x32_bf16 v[88:91], v[210:213], v[194:197], v[88:91]
	v_mfma_f32_16x16x32_bf16 v[80:83], v[218:221], v[194:197], v[80:83]
	v_mfma_f32_16x16x32_bf16 v[72:75], v[210:213], v[202:205], v[72:75]
	v_mfma_f32_16x16x32_bf16 v[64:67], v[218:221], v[202:205], v[64:67]
	s_setprio 0
	s_barrier
; __device__ __forceinline__ u32x4 pack8(const float* f) { u32x4 w; w.x = pk2(f[0], f[1]); w.y = pk2(f[2], f[3]); w.z = pk2(f[4], f[5]); w.w = pk2(f[6], f[7]); return w; }
; #define PG8_STAGE(bufoff, gbase, voff) do { _Pragma("unroll") for (int _i = 0; _i < 2; ++_i) \
;         __builtin_amdgcn_global_load_lds((const unsigned*)((const char*)(gbase) + (voff)[_i]), (LAS unsigned*)(lds + (bufoff) + ldsw + _i * 8192), 16, 0, 0); } while (0)
; #define PG8_LDA(dst, b, h) do { _Pragma("unroll") for (int m = 0; m < 4; ++m) _Pragma("unroll") for (int k = 0; k < 2; ++k) dst[m][k] = *(const LAS bf16x8*)(lds + PG8_SA(b, h) + aoff + m * 2048 + k * 1024); } while (0)
; #define PG8_WAIT_V(n) asm volatile("s_waitcnt vmcnt(" #n ")" ::: "memory")
; #define PG8_WAIT_L(n) asm volatile("s_waitcnt lgkmcnt(" #n ")" ::: "memory")
; #define PG8_BAR __builtin_amdgcn_s_barrier()
; template <class Epi, class Sched>
; __device__ __forceinline__ void gemm_phase(LAS unsigned char* lds, const Gemm g, const Sched& S, const Epi& E) {
;     ...
;             PG8_LDA(At, 1, 1); PG8_STAGE(PG8_SA(1, 0), a3, voffA);
;             PG8_BAR; PG8_WAIT_L(0); if constexpr (!Epi::DIAG) PG8_MMA(1, 0, At, B0); PG8_BAR; PG8_SCHED;
;             PG8_STAGE(PG8_SB(1, 1), b3 + hstepB, voffB);
;             PG8_WAIT_V(6); PG8_BAR; PG8_MMA(1, 1, At, B1); PG8_BAR;
;     __device__ __forceinline__ void operator()(const Acc& acc, const Unit& u, int wr, int wc, int fr, int fq) const {
;         const int row0 = u.pm * BM + wr * 64 + fr, col0 = u.pn * HALF + wc * 32 + 8 * fq;
; #pragma unroll
;         for (int ai = 0; ai < 2; ++ai)
; #pragma unroll
;             for (int m = 0; m < 4; ++m) { float v[8];
; #pragma unroll
;                 for (int n = 0; n < 2; ++n) {
;                     const f32x4 gt = acc[ai][0][m][n], arg = gt * (-1.4426950408889634f), gu = gt * acc[ai][1][m][n];
;                     f32x4 t;
; #pragma unroll
;                     for (int j = 0; j < 4; ++j) t[j] = __builtin_amdgcn_exp2f(arg[j]);
;                     t = t + 1.0f;
; #pragma unroll
;                     for (int j = 0; j < 4; ++j) t[j] = __builtin_amdgcn_rcpf(t[j]);
;                     const f32x4 r = gu * t;
; #pragma unroll
;                     for (int j = 0; j < 4; ++j) v[4 * n + j] = r[j]; }
;                 *(u32x4*)(O + (size_t)(row0 + ai * HALF + m * 16) * DFF + col0) = pack8(v); }
	ds_read_b128 v[170:173], v148 offset:49152
	ds_read_b128 v[174:177], v148 offset:50176
	ds_read_b128 v[178:181], v148 offset:51200
	ds_read_b128 v[186:189], v148 offset:52224
	ds_read_b128 v[190:193], v148 offset:53248
	ds_read_b128 v[194:197], v148 offset:54272
	ds_read_b128 v[198:201], v148 offset:55296
	ds_read_b128 v[202:205], v148 offset:56320
	v_lshl_add_u64 v[158:159], v[158:159], 0, s[10:11]
	s_mov_b32 m0, s27
	s_nop 0
	global_load_lds_dwordx4 v[158:159], off
	v_lshl_add_u64 v[158:159], v[182:183], 0, s[10:11]
	s_add_i32 m0, s27, 0x2000
	s_nop 0
	global_load_lds_dwordx4 v[158:159], off
	s_mov_b32 m0, s42
	v_lshl_add_u64 v[158:159], v[222:223], 0, s[10:11]
	global_load_lds_dwordx4 v[158:159], off
	v_lshl_add_u64 v[158:159], v[224:225], 0, s[10:11]
	s_mov_b32 m0, s43
	s_nop 0
	global_load_lds_dwordx4 v[158:159], off
	s_add_u32 s24, s24, 0x80080
	s_addc_u32 s25, s25, 0
	s_add_i32 s26, s26, s34
	v_lshl_add_u64 v[230:231], s[24:25], 0, v[130:131]
	s_mov_b32 m0, s26
	s_nop 0
	global_load_lds_dwordx4 v[230:231], off
	v_lshl_add_u64 v[230:231], s[24:25], 0, v[134:135]
	s_add_i32 m0, s26, 0x2000
	s_nop 0
	global_load_lds_dwordx4 v[230:231], off
	s_waitcnt vmcnt(8)
	s_barrier
	s_waitcnt lgkmcnt(0)
	s_setprio 1
	v_mfma_f32_16x16x32_bf16 v[60:63], v[150:153], v[170:173], v[60:63]
	v_mfma_f32_16x16x32_bf16 v[52:55], v[162:165], v[170:173], v[52:55]
	v_mfma_f32_16x16x32_bf16 v[44:47], v[150:153], v[178:181], v[44:47]
	v_mfma_f32_16x16x32_bf16 v[36:39], v[162:165], v[178:181], v[36:39]
	v_mfma_f32_16x16x32_bf16 v[28:31], v[150:153], v[190:193], v[28:31]
	v_mfma_f32_16x16x32_bf16 v[20:23], v[162:165], v[190:193], v[20:23]
	v_mfma_f32_16x16x32_bf16 v[12:15], v[150:153], v[198:201], v[12:15]
	v_mfma_f32_16x16x32_bf16 v[4:7], v[162:165], v[198:201], v[4:7]
	v_mfma_f32_16x16x32_bf16 v[60:63], v[154:157], v[174:177], v[60:63]
	v_mfma_f32_16x16x32_bf16 v[52:55], v[166:169], v[174:177], v[52:55]
	v_mfma_f32_16x16x32_bf16 v[44:47], v[154:157], v[186:189], v[44:47]
	v_mfma_f32_16x16x32_bf16 v[36:39], v[166:169], v[186:189], v[36:39]
	v_mfma_f32_16x16x32_bf16 v[28:31], v[154:157], v[194:197], v[28:31]
	v_mfma_f32_16x16x32_bf16 v[20:23], v[166:169], v[194:197], v[20:23]
	v_mfma_f32_16x16x32_bf16 v[12:15], v[154:157], v[202:205], v[12:15]
	v_mfma_f32_16x16x32_bf16 v[4:7], v[166:169], v[202:205], v[4:7]
	v_mfma_f32_16x16x32_bf16 v[56:59], v[206:209], v[170:173], v[56:59]
	v_mfma_f32_16x16x32_bf16 v[48:51], v[214:217], v[170:173], v[48:51]
	v_mfma_f32_16x16x32_bf16 v[40:43], v[206:209], v[178:181], v[40:43]
	v_mfma_f32_16x16x32_bf16 v[32:35], v[214:217], v[178:181], v[32:35]
	v_mfma_f32_16x16x32_bf16 v[24:27], v[206:209], v[190:193], v[24:27]
	v_mfma_f32_16x16x32_bf16 v[16:19], v[214:217], v[190:193], v[16:19]
	v_mfma_f32_16x16x32_bf16 v[8:11], v[206:209], v[198:201], v[8:11]
	v_mfma_f32_16x16x32_bf16 v[0:3], v[214:217], v[198:201], v[0:3]
	v_mfma_f32_16x16x32_bf16 v[56:59], v[210:213], v[174:177], v[56:59]
	v_mfma_f32_16x16x32_bf16 v[48:51], v[218:221], v[174:177], v[48:51]
	v_mfma_f32_16x16x32_bf16 v[40:43], v[210:213], v[186:189], v[40:43]
	v_mfma_f32_16x16x32_bf16 v[32:35], v[218:221], v[186:189], v[32:35]
	v_mfma_f32_16x16x32_bf16 v[24:27], v[210:213], v[194:197], v[24:27]
	v_mfma_f32_16x16x32_bf16 v[16:19], v[218:221], v[194:197], v[16:19]
	v_mfma_f32_16x16x32_bf16 v[8:11], v[210:213], v[202:205], v[8:11]
	v_mfma_f32_16x16x32_bf16 v[0:3], v[218:221], v[202:205], v[0:3]
	s_setprio 0
	s_add_i32 s52, s52, 2
	s_add_u32 s22, s22, 0x100
	s_addc_u32 s23, s23, 0
	s_add_u32 s50, s50, 0x100
	s_addc_u32 s51, s51, 0
	s_cmp_gt_u32 s52, 29
	s_barrier
	s_cbranch_scc0 .LBB0_1843
	v_mul_f32_e32 v153, 0xbfb8aa3b, v126
	v_exp_f32_e32 v154, v153
	v_mul_f32_e32 v153, 0xbfb8aa3b, v127
	v_mul_f32_e32 v151, 0xbfb8aa3b, v124
	v_exp_f32_e32 v155, v153
	v_exp_f32_e32 v152, v151
	v_mul_f32_e32 v151, 0xbfb8aa3b, v125
	v_pk_mul_f32 v[120:121], v[120:121], v[124:125]
	v_mul_f32_e32 v124, 0xbfb8aa3b, v116
	v_mul_f32_e32 v125, 0xbfb8aa3b, v117
	v_pk_mul_f32 v[122:123], v[122:123], v[126:127]
	v_exp_f32_e32 v124, v124
	v_mul_f32_e32 v126, 0xbfb8aa3b, v118
	v_mul_f32_e32 v127, 0xbfb8aa3b, v119
	v_exp_f32_e32 v125, v125
	v_exp_f32_e32 v153, v151
	v_exp_f32_e32 v126, v126
	v_exp_f32_e32 v127, v127
	v_pk_add_f32 v[154:155], v[154:155], 1.0 op_sel_hi:[1,0]
	v_pk_add_f32 v[124:125], v[124:125], 1.0 op_sel_hi:[1,0]
	v_rcp_f32_e32 v154, v154
	v_rcp_f32_e32 v155, v155
	v_pk_add_f32 v[152:153], v[152:153], 1.0 op_sel_hi:[1,0]
	v_pk_add_f32 v[126:127], v[126:127], 1.0 op_sel_hi:[1,0]
	v_rcp_f32_e32 v124, v124
	v_rcp_f32_e32 v125, v125
	v_rcp_f32_e32 v152, v152
	v_rcp_f32_e32 v153, v153
	v_rcp_f32_e32 v126, v126
	v_rcp_f32_e32 v127, v127
	v_pk_mul_f32 v[122:123], v[122:123], v[154:155]
	v_pk_mul_f32 v[112:113], v[112:113], v[116:117]
	v_cvt_pk_bf16_f32 v117, v122, v123
	v_mul_f32_e32 v122, 0xbfb8aa3b, v108
	v_mul_f32_e32 v123, 0xbfb8aa3b, v109
	v_lshl_or_b32 v156, s47, 7, v146
	v_pk_mul_f32 v[114:115], v[114:115], v[118:119]
	v_pk_mul_f32 v[112:113], v[112:113], v[124:125]
	v_exp_f32_e32 v122, v122
	v_mul_f32_e32 v124, 0xbfb8aa3b, v110
	v_mul_f32_e32 v125, 0xbfb8aa3b, v111
	v_exp_f32_e32 v123, v123
	v_pk_mul_f32 v[106:107], v[106:107], v[110:111]
	v_pk_mul_f32 v[104:105], v[104:105], v[108:109]
	v_mul_f32_e32 v108, 0xbfb8aa3b, v100
	v_mul_f32_e32 v109, 0xbfb8aa3b, v101
	v_mul_f32_e32 v110, 0xbfb8aa3b, v102
	v_mul_f32_e32 v111, 0xbfb8aa3b, v103
	v_lshl_add_u32 v150, s20, 8, v144
	v_ashrrev_i32_e32 v157, 31, v156
	v_pk_mul_f32 v[120:121], v[120:121], v[152:153]
	v_pk_mul_f32 v[114:115], v[114:115], v[126:127]
	v_cvt_pk_bf16_f32 v118, v112, v113
	v_mov_b64_e32 v[112:113], s[8:9]
	v_exp_f32_e32 v108, v108
; __device__ __forceinline__ u32x4 pack8(const float* f) { u32x4 w; w.x = pk2(f[0], f[1]); w.y = pk2(f[2], f[3]); w.z = pk2(f[4], f[5]); w.w = pk2(f[6], f[7]); return w; }
;     __device__ __forceinline__ void operator()(const Acc& acc, const Unit& u, int wr, int wc, int fr, int fq) const {
;     ...
; #pragma unroll
;         for (int ai = 0; ai < 2; ++ai)
; #pragma unroll
;             for (int m = 0; m < 4; ++m) { float v[8];
; #pragma unroll
;                 for (int n = 0; n < 2; ++n) {
;                     const f32x4 gt = acc[ai][0][m][n], arg = gt * (-1.4426950408889634f), gu = gt * acc[ai][1][m][n];
;                     f32x4 t;
; #pragma unroll
;                     for (int j = 0; j < 4; ++j) t[j] = __builtin_amdgcn_exp2f(arg[j]);
;                     t = t + 1.0f;
; #pragma unroll
;                     for (int j = 0; j < 4; ++j) t[j] = __builtin_amdgcn_rcpf(t[j]);
;                     const f32x4 r = gu * t;
; #pragma unroll
;                     for (int j = 0; j < 4; ++j) v[4 * n + j] = r[j]; }
;                 *(u32x4*)(O + (size_t)(row0 + ai * HALF + m * 16) * DFF + col0) = pack8(v); }
	v_exp_f32_e32 v110, v110
	v_exp_f32_e32 v111, v111
	v_exp_f32_e32 v109, v109
	v_cvt_pk_bf16_f32 v116, v120, v121
	v_cvt_pk_bf16_f32 v119, v114, v115
	v_mad_i64_i32 v[120:121], s[22:23], v150, s46, v[112:113]
	v_lshlrev_b64 v[114:115], 1, v[156:157]
	v_lshl_add_u64 v[120:121], v[120:121], 0, v[114:115]
	global_store_dwordx4 v[120:121], v[116:119], off
	v_exp_f32_e32 v124, v124
	v_exp_f32_e32 v125, v125
	v_pk_add_f32 v[118:119], v[122:123], 1.0 op_sel_hi:[1,0]
	v_pk_add_f32 v[110:111], v[110:111], 1.0 op_sel_hi:[1,0]
	v_rcp_f32_e32 v118, v118
	v_rcp_f32_e32 v119, v119
	v_pk_add_f32 v[108:109], v[108:109], 1.0 op_sel_hi:[1,0]
	v_rcp_f32_e32 v110, v110
	v_rcp_f32_e32 v108, v108
	v_rcp_f32_e32 v109, v109
	v_rcp_f32_e32 v111, v111
	v_pk_add_f32 v[116:117], v[124:125], 1.0 op_sel_hi:[1,0]
	v_pk_mul_f32 v[104:105], v[104:105], v[118:119]
	v_pk_mul_f32 v[98:99], v[98:99], v[102:103]
	v_pk_mul_f32 v[96:97], v[96:97], v[100:101]
	v_rcp_f32_e32 v116, v116
	v_rcp_f32_e32 v117, v117
	v_pk_mul_f32 v[100:101], v[96:97], v[108:109]
	v_pk_mul_f32 v[102:103], v[98:99], v[110:111]
	v_cvt_pk_bf16_f32 v96, v104, v105
	v_mul_f32_e32 v104, 0xbfb8aa3b, v94
	v_mul_f32_e32 v105, 0xbfb8aa3b, v95
	v_pk_mul_f32 v[90:91], v[90:91], v[94:95]
	v_mul_f32_e32 v94, 0xbfb8aa3b, v86
	v_mul_f32_e32 v95, 0xbfb8aa3b, v87
	v_cvt_pk_bf16_f32 v99, v102, v103
	v_mul_f32_e32 v102, 0xbfb8aa3b, v92
	v_mul_f32_e32 v103, 0xbfb8aa3b, v93
	v_exp_f32_e32 v94, v94
	v_exp_f32_e32 v95, v95
	v_exp_f32_e32 v102, v102
	v_exp_f32_e32 v103, v103
	v_pk_mul_f32 v[88:89], v[88:89], v[92:93]
	v_mul_f32_e32 v92, 0xbfb8aa3b, v84
	v_mul_f32_e32 v93, 0xbfb8aa3b, v85
	v_cvt_pk_bf16_f32 v98, v100, v101
	v_or_b32_e32 v100, 16, v150
	v_exp_f32_e32 v92, v92
	v_exp_f32_e32 v93, v93
	v_pk_mul_f32 v[106:107], v[106:107], v[116:117]
	v_mad_i64_i32 v[100:101], s[22:23], v100, s46, v[112:113]
	v_cvt_pk_bf16_f32 v97, v106, v107
	v_exp_f32_e32 v104, v104
	v_exp_f32_e32 v105, v105
	v_lshl_add_u64 v[100:101], v[100:101], 0, v[114:115]
	v_pk_add_f32 v[94:95], v[94:95], 1.0 op_sel_hi:[1,0]
	global_store_dwordx4 v[100:101], v[96:99], off
	v_rcp_f32_e32 v94, v94
	v_rcp_f32_e32 v95, v95
	v_pk_add_f32 v[98:99], v[102:103], 1.0 op_sel_hi:[1,0]
	v_pk_add_f32 v[92:93], v[92:93], 1.0 op_sel_hi:[1,0]
	v_rcp_f32_e32 v98, v98
	v_rcp_f32_e32 v99, v99
	v_rcp_f32_e32 v92, v92
	v_rcp_f32_e32 v93, v93
	v_pk_add_f32 v[96:97], v[104:105], 1.0 op_sel_hi:[1,0]
	v_pk_mul_f32 v[82:83], v[82:83], v[86:87]
	v_rcp_f32_e32 v96, v96
	v_rcp_f32_e32 v97, v97
	v_pk_mul_f32 v[86:87], v[82:83], v[94:95]
	v_pk_mul_f32 v[88:89], v[88:89], v[98:99]
	v_pk_mul_f32 v[80:81], v[80:81], v[84:85]
	v_cvt_pk_bf16_f32 v83, v86, v87
	v_mul_f32_e32 v86, 0xbfb8aa3b, v76
	v_mul_f32_e32 v87, 0xbfb8aa3b, v77
	v_pk_mul_f32 v[84:85], v[80:81], v[92:93]
	v_cvt_pk_bf16_f32 v80, v88, v89
	v_exp_f32_e32 v86, v86
	v_mul_f32_e32 v88, 0xbfb8aa3b, v78
	v_mul_f32_e32 v89, 0xbfb8aa3b, v79
	v_exp_f32_e32 v87, v87
	v_pk_mul_f32 v[74:75], v[74:75], v[78:79]
	v_pk_mul_f32 v[72:73], v[72:73], v[76:77]
	v_mul_f32_e32 v76, 0xbfb8aa3b, v68
	v_mul_f32_e32 v77, 0xbfb8aa3b, v69
	v_mul_f32_e32 v78, 0xbfb8aa3b, v70
	v_mul_f32_e32 v79, 0xbfb8aa3b, v71
	v_cvt_pk_bf16_f32 v82, v84, v85
	v_or_b32_e32 v84, 32, v150
	v_exp_f32_e32 v76, v76
	v_exp_f32_e32 v78, v78
	v_exp_f32_e32 v79, v79
	v_exp_f32_e32 v77, v77
	v_pk_mul_f32 v[90:91], v[90:91], v[96:97]
	v_mad_i64_i32 v[84:85], s[22:23], v84, s46, v[112:113]
	v_cvt_pk_bf16_f32 v81, v90, v91
	v_lshl_add_u64 v[84:85], v[84:85], 0, v[114:115]
	global_store_dwordx4 v[84:85], v[80:83], off
	v_exp_f32_e32 v88, v88
	v_exp_f32_e32 v89, v89
	v_pk_add_f32 v[82:83], v[86:87], 1.0 op_sel_hi:[1,0]
	v_pk_add_f32 v[78:79], v[78:79], 1.0 op_sel_hi:[1,0]
	v_rcp_f32_e32 v82, v82
	v_rcp_f32_e32 v83, v83
	v_pk_add_f32 v[76:77], v[76:77], 1.0 op_sel_hi:[1,0]
	v_rcp_f32_e32 v78, v78
	v_rcp_f32_e32 v76, v76
	v_rcp_f32_e32 v77, v77
	v_rcp_f32_e32 v79, v79
	v_pk_add_f32 v[80:81], v[88:89], 1.0 op_sel_hi:[1,0]
	v_pk_mul_f32 v[72:73], v[72:73], v[82:83]
	v_pk_mul_f32 v[66:67], v[66:67], v[70:71]
	v_pk_mul_f32 v[64:65], v[64:65], v[68:69]
	v_rcp_f32_e32 v80, v80
	v_rcp_f32_e32 v81, v81
	v_pk_mul_f32 v[68:69], v[64:65], v[76:77]
	v_pk_mul_f32 v[70:71], v[66:67], v[78:79]
	v_cvt_pk_bf16_f32 v64, v72, v73
	v_mul_f32_e32 v72, 0xbfb8aa3b, v62
	v_mul_f32_e32 v73, 0xbfb8aa3b, v63
	v_pk_mul_f32 v[58:59], v[58:59], v[62:63]
	v_mul_f32_e32 v62, 0xbfb8aa3b, v54
	v_mul_f32_e32 v63, 0xbfb8aa3b, v55
	v_cvt_pk_bf16_f32 v67, v70, v71
	v_mul_f32_e32 v70, 0xbfb8aa3b, v60
	v_mul_f32_e32 v71, 0xbfb8aa3b, v61
	v_exp_f32_e32 v62, v62
	v_exp_f32_e32 v63, v63
	v_exp_f32_e32 v70, v70
	v_exp_f32_e32 v71, v71
	v_pk_mul_f32 v[56:57], v[56:57], v[60:61]
	v_mul_f32_e32 v60, 0xbfb8aa3b, v52
	v_mul_f32_e32 v61, 0xbfb8aa3b, v53
	v_cvt_pk_bf16_f32 v66, v68, v69
	v_or_b32_e32 v68, 48, v150
	v_exp_f32_e32 v60, v60
	v_exp_f32_e32 v61, v61
	v_pk_mul_f32 v[74:75], v[74:75], v[80:81]
	v_mad_i64_i32 v[68:69], s[22:23], v68, s46, v[112:113]
	v_cvt_pk_bf16_f32 v65, v74, v75
	v_lshl_add_u64 v[68:69], v[68:69], 0, v[114:115]
	v_exp_f32_e32 v72, v72
	v_exp_f32_e32 v73, v73
	v_pk_add_f32 v[62:63], v[62:63], 1.0 op_sel_hi:[1,0]
	global_store_dwordx4 v[68:69], v[64:67], off
	v_rcp_f32_e32 v62, v62
	v_rcp_f32_e32 v63, v63
	v_pk_add_f32 v[66:67], v[70:71], 1.0 op_sel_hi:[1,0]
	v_pk_add_f32 v[60:61], v[60:61], 1.0 op_sel_hi:[1,0]
	v_rcp_f32_e32 v66, v66
	v_rcp_f32_e32 v67, v67
	v_rcp_f32_e32 v60, v60
	v_rcp_f32_e32 v61, v61
	v_pk_add_f32 v[64:65], v[72:73], 1.0 op_sel_hi:[1,0]
; __device__ __forceinline__ u32x4 pack8(const float* f) { u32x4 w; w.x = pk2(f[0], f[1]); w.y = pk2(f[2], f[3]); w.z = pk2(f[4], f[5]); w.w = pk2(f[6], f[7]); return w; }
; #define PG8_WAIT_V(n) asm volatile("s_waitcnt vmcnt(" #n ")" ::: "memory")
; #define PG8_BAR __builtin_amdgcn_s_barrier()
; template <class Epi, class Sched>
; __device__ __forceinline__ void gemm_phase(LAS unsigned char* lds, const Gemm g, const Sched& S, const Epi& E) {
;     ...
;         cur = nxt; cA = nA; cB = nB; ++ui;
;     }
;     PG8_WAIT_V(0);
;     if (wr == 0) PG8_BAR;
;     PG8_BAR;
;     __device__ __forceinline__ void operator()(const Acc& acc, const Unit& u, int wr, int wc, int fr, int fq) const {
;     ...
; #pragma unroll
;         for (int ai = 0; ai < 2; ++ai)
; #pragma unroll
;             for (int m = 0; m < 4; ++m) { float v[8];
; #pragma unroll
;                 for (int n = 0; n < 2; ++n) {
;                     const f32x4 gt = acc[ai][0][m][n], arg = gt * (-1.4426950408889634f), gu = gt * acc[ai][1][m][n];
;                     f32x4 t;
; #pragma unroll
;                     for (int j = 0; j < 4; ++j) t[j] = __builtin_amdgcn_exp2f(arg[j]);
;                     t = t + 1.0f;
; #pragma unroll
;                     for (int j = 0; j < 4; ++j) t[j] = __builtin_amdgcn_rcpf(t[j]);
;                     const f32x4 r = gu * t;
; #pragma unroll
;                     for (int j = 0; j < 4; ++j) v[4 * n + j] = r[j]; }
;                 *(u32x4*)(O + (size_t)(row0 + ai * HALF + m * 16) * DFF + col0) = pack8(v); }
	v_pk_mul_f32 v[50:51], v[50:51], v[54:55]
	v_rcp_f32_e32 v64, v64
	v_rcp_f32_e32 v65, v65
	v_pk_mul_f32 v[54:55], v[50:51], v[62:63]
	v_pk_mul_f32 v[56:57], v[56:57], v[66:67]
	v_pk_mul_f32 v[48:49], v[48:49], v[52:53]
	v_cvt_pk_bf16_f32 v51, v54, v55
	v_mul_f32_e32 v54, 0xbfb8aa3b, v44
	v_mul_f32_e32 v55, 0xbfb8aa3b, v45
	v_pk_mul_f32 v[52:53], v[48:49], v[60:61]
	v_cvt_pk_bf16_f32 v48, v56, v57
	v_exp_f32_e32 v54, v54
	v_mul_f32_e32 v56, 0xbfb8aa3b, v46
	v_mul_f32_e32 v57, 0xbfb8aa3b, v47
	v_exp_f32_e32 v55, v55
	v_pk_mul_f32 v[42:43], v[42:43], v[46:47]
	v_pk_mul_f32 v[40:41], v[40:41], v[44:45]
	v_mul_f32_e32 v44, 0xbfb8aa3b, v36
	v_mul_f32_e32 v45, 0xbfb8aa3b, v37
	v_mul_f32_e32 v46, 0xbfb8aa3b, v38
	v_mul_f32_e32 v47, 0xbfb8aa3b, v39
	v_add_u32_e32 v68, 0x80, v150
	v_exp_f32_e32 v44, v44
	v_exp_f32_e32 v46, v46
	v_exp_f32_e32 v47, v47
	v_exp_f32_e32 v45, v45
	v_pk_mul_f32 v[58:59], v[58:59], v[64:65]
	v_cvt_pk_bf16_f32 v50, v52, v53
	v_mad_i64_i32 v[52:53], s[22:23], v68, s46, v[112:113]
	v_cvt_pk_bf16_f32 v49, v58, v59
	v_lshl_add_u64 v[52:53], v[52:53], 0, v[114:115]
	global_store_dwordx4 v[52:53], v[48:51], off
	v_exp_f32_e32 v56, v56
	v_exp_f32_e32 v57, v57
	v_pk_add_f32 v[50:51], v[54:55], 1.0 op_sel_hi:[1,0]
	v_pk_add_f32 v[46:47], v[46:47], 1.0 op_sel_hi:[1,0]
	v_rcp_f32_e32 v50, v50
	v_rcp_f32_e32 v51, v51
	v_pk_add_f32 v[44:45], v[44:45], 1.0 op_sel_hi:[1,0]
	v_rcp_f32_e32 v46, v46
	v_rcp_f32_e32 v44, v44
	v_rcp_f32_e32 v45, v45
	v_rcp_f32_e32 v47, v47
	v_pk_add_f32 v[48:49], v[56:57], 1.0 op_sel_hi:[1,0]
	v_pk_mul_f32 v[40:41], v[40:41], v[50:51]
	v_pk_mul_f32 v[34:35], v[34:35], v[38:39]
	v_pk_mul_f32 v[32:33], v[32:33], v[36:37]
	v_rcp_f32_e32 v48, v48
	v_rcp_f32_e32 v49, v49
	v_pk_mul_f32 v[36:37], v[32:33], v[44:45]
	v_pk_mul_f32 v[38:39], v[34:35], v[46:47]
	v_cvt_pk_bf16_f32 v32, v40, v41
	v_mul_f32_e32 v40, 0xbfb8aa3b, v30
	v_mul_f32_e32 v41, 0xbfb8aa3b, v31
	v_pk_mul_f32 v[26:27], v[26:27], v[30:31]
	v_mul_f32_e32 v30, 0xbfb8aa3b, v22
	v_mul_f32_e32 v31, 0xbfb8aa3b, v23
	v_cvt_pk_bf16_f32 v35, v38, v39
	v_mul_f32_e32 v38, 0xbfb8aa3b, v28
	v_mul_f32_e32 v39, 0xbfb8aa3b, v29
	v_exp_f32_e32 v30, v30
	v_exp_f32_e32 v31, v31
	v_exp_f32_e32 v38, v38
	v_exp_f32_e32 v39, v39
	v_pk_mul_f32 v[24:25], v[24:25], v[28:29]
	v_mul_f32_e32 v28, 0xbfb8aa3b, v20
	v_mul_f32_e32 v29, 0xbfb8aa3b, v21
	v_cvt_pk_bf16_f32 v34, v36, v37
	v_add_u32_e32 v36, 0x90, v150
	v_exp_f32_e32 v28, v28
	v_exp_f32_e32 v29, v29
	v_pk_mul_f32 v[42:43], v[42:43], v[48:49]
	v_mad_i64_i32 v[36:37], s[22:23], v36, s46, v[112:113]
	v_cvt_pk_bf16_f32 v33, v42, v43
	v_lshl_add_u64 v[36:37], v[36:37], 0, v[114:115]
	v_pk_add_f32 v[30:31], v[30:31], 1.0 op_sel_hi:[1,0]
	global_store_dwordx4 v[36:37], v[32:35], off
	v_rcp_f32_e32 v30, v30
	v_rcp_f32_e32 v31, v31
	v_pk_add_f32 v[34:35], v[38:39], 1.0 op_sel_hi:[1,0]
	v_exp_f32_e32 v40, v40
	v_exp_f32_e32 v41, v41
	v_rcp_f32_e32 v34, v34
	v_rcp_f32_e32 v35, v35
	v_pk_add_f32 v[28:29], v[28:29], 1.0 op_sel_hi:[1,0]
	v_pk_mul_f32 v[18:19], v[18:19], v[22:23]
	v_rcp_f32_e32 v28, v28
	v_rcp_f32_e32 v29, v29
	v_pk_mul_f32 v[22:23], v[18:19], v[30:31]
	v_pk_add_f32 v[32:33], v[40:41], 1.0 op_sel_hi:[1,0]
	v_pk_mul_f32 v[24:25], v[24:25], v[34:35]
	v_pk_mul_f32 v[16:17], v[16:17], v[20:21]
	v_cvt_pk_bf16_f32 v19, v22, v23
	v_mul_f32_e32 v22, 0xbfb8aa3b, v12
	v_mul_f32_e32 v23, 0xbfb8aa3b, v13
	v_pk_mul_f32 v[8:9], v[8:9], v[12:13]
	v_mul_f32_e32 v12, 0xbfb8aa3b, v4
	v_mul_f32_e32 v13, 0xbfb8aa3b, v5
	v_rcp_f32_e32 v32, v32
	v_rcp_f32_e32 v33, v33
	v_pk_mul_f32 v[20:21], v[16:17], v[28:29]
	v_cvt_pk_bf16_f32 v16, v24, v25
	v_mul_f32_e32 v24, 0xbfb8aa3b, v14
	v_mul_f32_e32 v25, 0xbfb8aa3b, v15
	v_pk_mul_f32 v[10:11], v[10:11], v[14:15]
	v_exp_f32_e32 v12, v12
	v_mul_f32_e32 v14, 0xbfb8aa3b, v6
	v_mul_f32_e32 v15, 0xbfb8aa3b, v7
	v_exp_f32_e32 v13, v13
	v_exp_f32_e32 v14, v14
	v_exp_f32_e32 v15, v15
	v_exp_f32_e32 v22, v22
	v_exp_f32_e32 v24, v24
	v_exp_f32_e32 v25, v25
	v_exp_f32_e32 v23, v23
	v_cvt_pk_bf16_f32 v18, v20, v21
	v_add_u32_e32 v20, 0xa0, v150
	v_pk_mul_f32 v[26:27], v[26:27], v[32:33]
	v_mad_i64_i32 v[20:21], s[22:23], v20, s46, v[112:113]
	v_pk_add_f32 v[12:13], v[12:13], 1.0 op_sel_hi:[1,0]
	v_cvt_pk_bf16_f32 v17, v26, v27
	v_lshl_add_u64 v[20:21], v[20:21], 0, v[114:115]
	v_pk_add_f32 v[14:15], v[14:15], 1.0 op_sel_hi:[1,0]
	v_rcp_f32_e32 v12, v12
	v_rcp_f32_e32 v13, v13
	global_store_dwordx4 v[20:21], v[16:19], off
	v_rcp_f32_e32 v14, v14
	v_rcp_f32_e32 v15, v15
	v_pk_add_f32 v[16:17], v[24:25], 1.0 op_sel_hi:[1,0]
	v_pk_add_f32 v[18:19], v[22:23], 1.0 op_sel_hi:[1,0]
	v_rcp_f32_e32 v16, v16
	v_rcp_f32_e32 v18, v18
	v_rcp_f32_e32 v19, v19
	v_rcp_f32_e32 v17, v17
	v_pk_mul_f32 v[0:1], v[0:1], v[4:5]
	v_pk_mul_f32 v[2:3], v[2:3], v[6:7]
	v_pk_mul_f32 v[4:5], v[0:1], v[12:13]
	v_pk_mul_f32 v[6:7], v[2:3], v[14:15]
	v_cvt_pk_bf16_f32 v2, v4, v5
	v_add_u32_e32 v4, 0xb0, v150
	v_pk_mul_f32 v[8:9], v[8:9], v[18:19]
	v_pk_mul_f32 v[10:11], v[10:11], v[16:17]
	v_mad_i64_i32 v[4:5], s[22:23], v4, s46, v[112:113]
	v_cvt_pk_bf16_f32 v0, v8, v9
	v_cvt_pk_bf16_f32 v1, v10, v11
	v_cvt_pk_bf16_f32 v3, v6, v7
	v_lshl_add_u64 v[4:5], v[4:5], 0, v[114:115]
	s_and_b64 vcc, exec, s[6:7]
	s_mov_b32 s47, s12
	s_mov_b32 s20, s14
	s_mov_b64 s[24:25], s[18:19]
	s_mov_b64 s[22:23], s[16:17]
	global_store_dwordx4 v[4:5], v[0:3], off
	s_cbranch_vccz .LBB0_1840
	s_waitcnt vmcnt(0)
	s_cmpk_gt_u32 s3, 0xff
	s_cbranch_scc1 .LBB0_1847
	s_barrier
